# sb attention fully dynamic: all items via per-XCD single-item queues (no static share)
# speedup vs baseline: 1.0004x; 1.0004x over previous
; __device__ __forceinline__ void run_phase(const Args& a, const int ph, LAS unsigned char* lds, const int tid, const int rpt) {
;     ...
;                       const int nstat = (4 * NGW <= 12 * 1024) ? 4 * NGW : 0;
;                       if (nstat) for (int it = 4 * gw; it < 4 * gw + 4; ++it) sb_item(hbuf, kmax2, mixed, vT, it, lane);
.LBB0_230:
.LBB0_231:
	v_readlane_b32 s1, v249, 49
	s_lshl_b32 s0, s1, 5
	s_cmpk_lt_i32 s1, 0x181
	s_mov_b32 s0, 0
	s_cmp_lg_u32 s0, 0
	v_writelane_b32 v249, s0, 54
	s_cbranch_scc0 .LBB0_552
	v_lshrrev_b32_e32 v0, 4, v248
	v_and_b32_e32 v122, 15, v168
	v_lshlrev_b32_e32 v120, 2, v0
	v_lshlrev_b32_e32 v1, 2, v248
	v_or_b32_e32 v143, 1, v120
	v_cmp_lt_u32_e32 vcc, v120, v122
	v_mov_b32_e32 v7, 0x3f80
	v_lshlrev_b32_e32 v124, 3, v0
	v_xor_b32_e32 v132, 64, v1
	v_xor_b32_e32 v133, 0x80, v1
	v_and_b32_e32 v1, 7, v168
	v_cndmask_b32_e64 v0, v7, 0, vcc
	v_cmp_lt_u32_e32 vcc, v143, v122
	v_or_b32_e32 v144, 2, v120
	v_lshrrev_b32_e32 v134, 3, v248
	v_lshlrev_b32_e32 v126, 3, v1
	v_mul_u32_u24_e32 v139, 0x440, v1
	v_cndmask_b32_e64 v1, 1.0, 0, vcc
	v_or_b32_e32 v145, 3, v120
	v_cmp_lt_u32_e32 vcc, v144, v122
	v_lshlrev_b32_e32 v2, 1, v134
	v_readlane_b32 s0, v249, 53
	v_or_b32_e32 v36, v1, v0
	v_cndmask_b32_e64 v1, v7, 0, vcc
	v_cmp_lt_u32_e32 vcc, v145, v122
	v_or_b32_e32 v140, 17, v120
	v_or_b32_e32 v146, 16, v122
	v_add3_u32 v151, s0, v2, v139
	v_cndmask_b32_e64 v2, 1.0, 0, vcc
	v_or_b32_e32 v141, 18, v120
	v_cmp_lt_u32_e32 vcc, v140, v146
	v_or_b32_e32 v37, v2, v1
	v_or_b32_e32 v142, 19, v120
	v_cndmask_b32_e64 v1, 1.0, 0, vcc
	v_cmp_lt_u32_e32 vcc, v141, v146
	v_or_b32_e32 v8, 48, v248
	v_or_b32_e32 v136, 16, v120
	v_or_b32_e32 v2, v1, v0
	v_cndmask_b32_e64 v0, v7, 0, vcc
	v_cmp_lt_u32_e32 vcc, v142, v146
	v_subrev_u32_e32 v147, 32, v8
	s_lshl_b32 s12, s16, 2
	v_cndmask_b32_e64 v1, 1.0, 0, vcc
	v_cmp_lt_u32_e32 vcc, v136, v147
	v_add_u32_e32 v152, s0, v124
	s_movk_i32 s0, 0x88
	v_cndmask_b32_e64 v4, v7, 0, vcc
	v_cmp_lt_u32_e32 vcc, v140, v147
	s_waitcnt vmcnt(0)
	v_mov_b32_e32 v9, 0x880
	v_mov_b32_e32 v123, v33
	v_cndmask_b32_e64 v5, 1.0, 0, vcc
	v_cmp_lt_u32_e32 vcc, v141, v147
	v_or_b32_e32 v6, v5, v4
	v_mov_b32_e32 v125, v33
	v_cndmask_b32_e64 v4, v7, 0, vcc
	v_cmp_lt_u32_e32 vcc, v142, v147
	v_mov_b32_e32 v127, v33
	v_lshlrev_b32_e32 v135, 2, v122
	v_cndmask_b32_e64 v5, 1.0, 0, vcc
	v_mov_b32_e32 v39, v38
	v_or_b32_e32 v3, v1, v0
	v_mov_b32_e32 v0, v33
	v_mov_b32_e32 v1, v33
	v_or_b32_e32 v7, v5, v4
	v_mov_b32_e32 v4, v33
	v_mov_b32_e32 v5, v33
	v_mul_u32_u24_e32 v148, 0x88, v122
	v_mad_u32_u24 v149, v122, s0, v9
	v_mul_u32_u24_e32 v150, 0x88, v8
	v_or_b32_e32 v137, 32, v120
	v_or_b32_e32 v138, 48, v120
	v_mov_b32_e32 v121, v33
	s_or_b32 s15, s12, 3
	s_branch .LBB0_234

; __device__ __forceinline__ void run_phase(const Args& a, const int ph, LAS unsigned char* lds, const int tid, const int rpt) {
;     ...
;                       for (;;) { int it0 = 0; if (lane == 0) it0 = (int)atomicAdd(qctr, 2u); it0 = nstat + __builtin_amdgcn_readfirstlane(it0); if (it0 >= 12 * 1024) break;
.LBB0_281:
	s_or_b64 exec, exec, s[0:1]
	v_readfirstlane_b32 s12, v4
	s_cmp_ge_u32 s12, 0x600
	s_cselect_b32 s12, 0x10000, s12
	v_readlane_b32 s98, v251, 37
	s_mul_i32 s98, s98, 0x600
	s_add_i32 s12, s12, s98
	v_readlane_b32 s0, v249, 54
	s_add_i32 s12, s12, s0
	s_mov_b64 s[0:1], -1
	s_cmpk_gt_i32 s12, 0x2fff
	s_mov_b32 s15, s12
	s_cbranch_scc0 .LBB0_283
	s_branch .LBB0_276
